# v36 with the attention-phase static priority raise on waves 0-3 instead of 4-7
# speedup vs baseline: 1.0066x; 1.0066x over previous
; __global__ void __launch_bounds__(NWAVES * 64) mega_fwd(Args a) {
;     ...
;         else if (kind == 3) attn_mix_phase(a, (char*)lds, l, rep == 1 ? PROBE_SKIP : 0);
;     ...
;         else if (kind == 3) attn_mix_phase(a, (char*)lds, l);
;     ...
;         else attn_cross_phase(a, (char*)lds, l);
.LBB0_202:
	s_andn2_b64 vcc, exec, s[4:5]
	s_cbranch_vccnz .LBB0_289
	v_readlane_b32 s2, v250, 2
	v_readlane_b32 s3, v250, 3
	s_andn2_b64 vcc, exec, s[2:3]
	s_cbranch_vccnz .LBB0_289
	v_readfirstlane_b32 s2, v198
	s_nop 3
	s_cmpk_ge_u32 s2, 0x100
	s_cbranch_scc1 .Lprio_att_done
	s_setprio 1
